# small 32-unit GEMM epilogue: 8 residual loads issued together, one wait (was load/wait/fma/store ladder)
# baseline (speedup 1.0000x reference)
; DEV int opaque_tid() { int t = threadIdx.x; asm volatile("" : "+v"(t)); return t; }
;     ...
;   const int tid = opaque_tid(), lane = tid & 63, h = lane >> 5, r = lane & 31;
;   const int nk = K >> 6;
;   const int cch = (tid & 7) ^ ((tid >> 4) & 7);
;   const u16* ga = A + (size_t)(tid >> 3) * lda + cch * 8;
;   const u16* gb = Bt + (size_t)(tid >> 3) * ldb + cch * 8;
;   char* lds_t = smem + tid * 16;
;   auto issue_piece = [&](int kt, int pc) {
;     char* st = lds_t + (kt % NSTG) * STAGE;
;     if (pc < 4)
;       __builtin_amdgcn_global_load_lds((const unsigned*)(ga + (size_t)(64 * pc) * lda + (size_t)kt * ksa), (unsigned __attribute__((address_space(3)))*)(st + pc * 8192), 16, 0, 0);
;     else
;       __builtin_amdgcn_global_load_lds((const unsigned*)(gb + (size_t)(64 * (pc - 4)) * ldb + (size_t)kt * ksb), (unsigned __attribute__((address_space(3)))*)(st + ABYTES + (pc - 4) * 8192), 16, 0, 0);
;   };
;   const int x = (r >> 1) & 7;
;   int xo[4];
; #pragma unroll
;   for (int s = 0; s < 4; ++s) xo[s] = (((2 * s + h) ^ x) << 4);
;   asm volatile("s_waitcnt vmcnt(0)" ::: "memory");
; #pragma unroll
;   for (int d = 0; d < DIST; ++d)
; #pragma unroll
;     for (int pc = 0; pc < NLD; ++pc) issue_piece(d, pc);
; DEV void phase_outproj(const Params& p, int l, int hf, char* smem) {
;     ...
;     for (int u = (int)gridDim.x - 1 - (int)blockIdx.x; u < 32; u += gridDim.x) {
;       const int mt = (u >> 4) * 33, nt64 = u & 15;
;       f32x16 acc[1][2];
; #pragma unroll
;       for (int j = 0; j < 2; ++j)
; #pragma unroll
;         for (int e = 0; e < 16; ++e) acc[0][j][e] = 0.f;
;       gemm_main<1, 2, 64, 3>(acc, Y + (size_t)mt * 256 * 1024, 1024, W + (size_t)nt64 * 64 * 1024, 1024, 1024, smem, wm * 64, wn * 32);
.LBB0_31:
	s_ashr_i32 s6, s3, 4
	s_mul_i32 s8, s6, 33
	s_ashr_i32 s9, s8, 31
	s_and_b32 s5, s3, 15
	s_lshl_b64 s[8:9], s[8:9], 19
	v_mov_b32_e32 v4, v147
	s_add_u32 s8, s14, s8
	s_addc_u32 s9, s15, s9
	v_lshrrev_b32_e32 v0, 4, v4
	s_lshl_b32 s7, s5, 17
	v_xor_b32_e32 v5, v0, v4
	v_ashrrev_i32_e32 v0, 3, v4
	s_add_u32 s10, s16, s7
	v_ashrrev_i32_e32 v1, 31, v0
	s_addc_u32 s11, s17, 0
	v_lshlrev_b64 v[0:1], 11, v[0:1]
	v_lshlrev_b32_e32 v5, 4, v5
	v_lshl_add_u32 v70, v4, 4, 0
	v_lshl_add_u64 v[2:3], s[10:11], 0, v[0:1]
	v_lshl_add_u64 v[0:1], s[8:9], 0, v[0:1]
	v_and_b32_e32 v144, 0x70, v5
	v_readfirstlane_b32 s25, v70
	v_add_u32_e32 v71, 0x2000, v70
	v_lshl_add_u64 v[32:33], v[0:1], 0, v[144:145]
	s_waitcnt vmcnt(0)
	s_mov_b32 m0, s25
	v_readfirstlane_b32 s24, v71
	v_add_u32_e32 v69, 0x4000, v70
	global_load_lds_dwordx4 v[32:33], off
	v_lshl_add_u64 v[0:1], v[32:33], 0, s[56:57]
	s_mov_b32 m0, s24
	v_readfirstlane_b32 s23, v69
	v_add_u32_e32 v68, 0x6000, v70
	global_load_lds_dwordx4 v[0:1], off
	v_lshl_add_u64 v[0:1], v[32:33], 0, s[82:83]
	s_mov_b32 m0, s23
	v_readfirstlane_b32 s22, v68
	v_add_u32_e32 v65, 0x8000, v70
	global_load_lds_dwordx4 v[0:1], off
	v_lshl_add_u64 v[0:1], v[32:33], 0, s[92:93]
	s_mov_b32 m0, s22
	v_readfirstlane_b32 s21, v65
	v_add_u32_e32 v56, 0xc000, v70
	v_lshl_add_u64 v[34:35], v[2:3], 0, v[144:145]
	global_load_lds_dwordx4 v[0:1], off
	s_mov_b32 m0, s21
	v_readfirstlane_b32 s20, v56
	v_add_u32_e32 v59, 0xe000, v70
	global_load_lds_dwordx4 v[34:35], off
	v_lshl_add_u64 v[0:1], v[32:33], 0, s[62:63]
	s_mov_b32 m0, s20
	v_readfirstlane_b32 s19, v59
	v_add_u32_e32 v57, 0x10000, v70
	global_load_lds_dwordx4 v[0:1], off
	v_lshl_add_u64 v[0:1], v[32:33], 0, s[64:65]
	s_mov_b32 m0, s19
	v_readfirstlane_b32 s18, v57
	v_add_u32_e32 v50, 0x12000, v70
	global_load_lds_dwordx4 v[0:1], off
	v_lshl_add_u64 v[0:1], v[32:33], 0, s[66:67]
	s_mov_b32 m0, s18
	v_readfirstlane_b32 s13, v50
	v_add_u32_e32 v49, 0x14000, v70
	global_load_lds_dwordx4 v[0:1], off
	v_lshl_add_u64 v[0:1], v[32:33], 0, s[76:77]
	s_mov_b32 m0, s13
	v_readfirstlane_b32 s12, v49
	v_lshl_add_u64 v[2:3], v[34:35], 0, s[62:63]
	global_load_lds_dwordx4 v[0:1], off
	s_mov_b32 m0, s12
	v_lshrrev_b32_e32 v0, 5, v4
	global_load_lds_dwordx4 v[2:3], off
	v_bfe_u32 v2, v4, 1, 3
	v_bfe_u32 v1, v4, 5, 1
	v_bitop3_b32 v0, v0, v2, 1 bitop3:0x6c
	v_lshlrev_b32_e32 v64, 4, v0
	v_bitop3_b32 v0, v1, v2, 2 bitop3:0x36
	v_lshlrev_b32_e32 v86, 4, v0
	v_bitop3_b32 v0, v1, v2, 4 bitop3:0x36
	v_lshlrev_b32_e32 v87, 4, v0
	v_and_b32_e32 v0, 31, v4
	v_or_b32_e32 v4, v0, v52
	v_or_b32_e32 v0, v0, v53
	v_lshlrev_b32_e32 v84, 7, v0
	v_add_u32_e32 v51, 0, v84
	v_add_u32_e32 v36, v51, v64
	v_bitop3_b32 v8, v1, v2, 6 bitop3:0x36
	s_waitcnt vmcnt(5)
	s_barrier
	ds_read_b128 v[0:3], v36 offset:32768
	v_lshlrev_b32_e32 v85, 7, v4
	v_add_u32_e32 v58, 0, v85
	v_add_u32_e32 v37, v58, v64
	ds_read_b128 v[4:7], v37
	v_lshlrev_b32_e32 v88, 4, v8
	ds_read_b128 v[8:11], v37 offset:4096
	v_lshl_add_u64 v[66:67], v[34:35], 0, s[78:79]
	v_add_u32_e32 v44, 0x18000, v70
	s_waitcnt lgkmcnt(0)
	v_mfma_f32_32x32x16_bf16 v[16:31], v[0:3], v[4:7], 0
	v_add_u32_e32 v45, 0x1a000, v70
	v_readfirstlane_b32 s9, v44
	v_lshl_add_u64 v[4:5], v[32:33], 0, s[78:79]
	s_mov_b32 m0, s9
	v_readfirstlane_b32 s7, v45
	v_lshl_add_u64 v[6:7], v[32:33], 0, s[94:95]
	global_load_lds_dwordx4 v[4:5], off
	s_mov_b32 m0, s7
	s_nop 0
	global_load_lds_dwordx4 v[6:7], off
	v_mfma_f32_32x32x16_bf16 v[0:15], v[0:3], v[8:11], 0
	v_add_u32_e32 v46, 0x1c000, v70
	s_mov_b64 s[10:11], 0x40100
	v_readfirstlane_b32 s8, v46
	v_lshl_add_u64 v[38:39], v[32:33], 0, s[10:11]
	s_mov_b32 m0, s8
	s_nop 0
	global_load_lds_dwordx4 v[38:39], off
	v_add_u32_e32 v39, v51, v86
	ds_read_b128 v[40:43], v39 offset:32768
	v_add_u32_e32 v38, v58, v86
	ds_read_b128 v[60:63], v38
	ds_read_b128 v[72:75], v38 offset:4096
	s_waitcnt lgkmcnt(0)
	v_mfma_f32_32x32x16_bf16 v[16:31], v[40:43], v[60:63], v[16:31]
	v_add_u32_e32 v47, 0x1e000, v70
	s_mov_b64 s[10:11], 0x60100
	v_lshl_add_u64 v[60:61], v[32:33], 0, s[10:11]
	v_readfirstlane_b32 s10, v47
	s_mov_b32 m0, s10
	s_nop 0
	global_load_lds_dwordx4 v[60:61], off
	v_mfma_f32_32x32x16_bf16 v[0:15], v[40:43], v[72:75], v[0:15]
	v_add_u32_e32 v48, 0x20000, v70
	s_nop 0
	v_readfirstlane_b32 s11, v48
	s_mov_b32 m0, s11
	s_nop 0
	global_load_lds_dwordx4 v[66:67], off
	v_add_u32_e32 v40, v58, v87
	v_add_u32_e32 v41, v51, v87
	ds_read_b128 v[60:63], v40
	ds_read_b128 v[72:75], v40 offset:4096
	ds_read_b128 v[76:79], v41 offset:32768
	v_add_u32_e32 v42, v51, v88
	v_add_u32_e32 v43, v58, v88
	s_add_i32 s26, 0, 0x14000
	v_add_u32_e32 v89, s26, v84
	v_add_u32_e32 v51, v89, v64
	v_lshl_add_u64 v[66:67], v[34:35], 0, s[42:43]
	s_waitcnt lgkmcnt(0)
	v_mfma_f32_32x32x16_bf16 v[16:31], v[76:79], v[60:63], v[16:31]
	ds_read_b128 v[60:63], v42 offset:32768
	v_mfma_f32_32x32x16_bf16 v[0:15], v[76:79], v[72:75], v[0:15]
	ds_read_b128 v[72:75], v43 offset:4096
	ds_read_b128 v[76:79], v43
	s_waitcnt vmcnt(5)
	s_barrier
; #define MFMA(a, b, c) __builtin_amdgcn_mfma_f32_32x32x16_bf16((a), (b), (c), 0, 0, 0)
;     ...
;     const bool pre = (kt + DIST < nk);
;     const char* base = smem + (kt % NSTG) * STAGE;
;     const char* pa = base + (wrow_act + r) * 128;
;     const char* pw = base + ABYTES + (wrow_w + r) * 128;
;     constexpr int NM = NI * MJ;
;     constexpr int PPS = (NLD + 1) / 2;
; #pragma unroll
;     for (int s = 0; s < 4; ++s) {
;       bf16x8 af[MJ], wf[NI];
; #pragma unroll
;       for (int j = 0; j < MJ; ++j) af[j] = *(const bf16x8*)(pa + j * 32 * 128 + xo[s]);
; #pragma unroll
;       for (int i = 0; i < NI; ++i) wf[i] = *(const bf16x8*)(pw + i * 32 * 128 + xo[s]);
; #pragma unroll
;       for (int m = 0; m < NM; ++m) {
;         const int i = m / MJ, j = m % MJ;
;         acc[i][j] = MFMA(wf[i], af[j], acc[i][j]);
;         if (s < 2 && NM >= PPS) {
;           constexpr int EVERY = (NM / PPS) > 0 ? (NM / PPS) : 1;
;           if ((m + 1) % EVERY == 0) {
;             const int pc = s * PPS + (m + 1) / EVERY - 1;
;             if ((m + 1) / EVERY <= PPS && pc < NLD) {
;               __builtin_amdgcn_sched_barrier(0);
;               if (pre) issue_piece(kt + DIST, pc);
;               __builtin_amdgcn_sched_barrier(0);
;             }
;           }
;         }
;         if (s < 2 && NM < PPS) {
;           const int slot = s * NM + m;
;           __builtin_amdgcn_sched_barrier(0);
; #pragma unroll
;           for (int pc = 0; pc < NLD; ++pc)
;             if ((pc * 2 * NM) / NLD == slot && pre) issue_piece(kt + DIST, pc);
;           __builtin_amdgcn_sched_barrier(0);
;         }
;       }
;     }
	s_waitcnt lgkmcnt(0)
	v_mfma_f32_32x32x16_bf16 v[16:31], v[60:63], v[76:79], v[16:31]
	v_mfma_f32_32x32x16_bf16 v[0:15], v[60:63], v[72:75], v[0:15]
	ds_read_b128 v[60:63], v37 offset:49152
	ds_read_b128 v[72:75], v37 offset:53248
	ds_read_b128 v[76:79], v51
	s_waitcnt lgkmcnt(0)
	v_mfma_f32_32x32x16_bf16 v[16:31], v[76:79], v[60:63], v[16:31]
	s_mov_b32 m0, s25
	v_lshl_add_u64 v[60:61], v[32:33], 0, s[42:43]
	s_mov_b64 s[26:27], 0x20180
	v_lshl_add_u64 v[62:63], v[32:33], 0, s[26:27]
	global_load_lds_dwordx4 v[60:61], off
	s_mov_b32 m0, s24
	s_nop 0
	global_load_lds_dwordx4 v[62:63], off
	v_mfma_f32_32x32x16_bf16 v[0:15], v[76:79], v[72:75], v[0:15]
	s_mov_b64 s[26:27], 0x40180
	v_lshl_add_u64 v[60:61], v[32:33], 0, s[26:27]
	s_mov_b32 m0, s23
	s_nop 0
	global_load_lds_dwordx4 v[60:61], off
	v_add_u32_e32 v58, v89, v86
	ds_read_b128 v[60:63], v58
	ds_read_b128 v[72:75], v38 offset:49152
	ds_read_b128 v[76:79], v38 offset:53248
	s_waitcnt lgkmcnt(0)
	v_mfma_f32_32x32x16_bf16 v[16:31], v[60:63], v[72:75], v[16:31]
	s_mov_b64 s[26:27], 0x60180
	v_lshl_add_u64 v[72:73], v[32:33], 0, s[26:27]
	s_mov_b32 m0, s22
	s_nop 0
	global_load_lds_dwordx4 v[72:73], off
	v_mfma_f32_32x32x16_bf16 v[0:15], v[60:63], v[76:79], v[0:15]
	s_mov_b32 m0, s21
	s_nop 0
	global_load_lds_dwordx4 v[66:67], off
	v_add_u32_e32 v60, v89, v87
	ds_read_b128 v[72:75], v40 offset:49152
	ds_read_b128 v[76:79], v40 offset:53248
	ds_read_b128 v[80:83], v60
	v_add_u32_e32 v61, v89, v88
	s_add_i32 s26, 0, 0x18000
	v_add_u32_e32 v89, s26, v85
	s_add_i32 s26, 0, 0x20000
	v_add_u32_e32 v90, s26, v84
	v_add_u32_e32 v62, v89, v64
	v_add_u32_e32 v63, v90, v64
	s_waitcnt lgkmcnt(0)
	v_mfma_f32_32x32x16_bf16 v[16:31], v[80:83], v[72:75], v[16:31]
	v_lshl_add_u64 v[84:85], v[34:35], 0, s[52:53]
	v_mfma_f32_32x32x16_bf16 v[0:15], v[80:83], v[76:79], v[0:15]
	ds_read_b128 v[72:75], v61
	ds_read_b128 v[76:79], v43 offset:53248
	ds_read_b128 v[80:83], v43 offset:49152
	s_waitcnt vmcnt(5)
	s_barrier
	s_waitcnt lgkmcnt(0)
	v_mfma_f32_32x32x16_bf16 v[16:31], v[72:75], v[80:83], v[16:31]
	v_mfma_f32_32x32x16_bf16 v[0:15], v[72:75], v[76:79], v[0:15]
	ds_read_b128 v[72:75], v62
	ds_read_b128 v[76:79], v62 offset:4096
	ds_read_b128 v[80:83], v63
	s_waitcnt lgkmcnt(0)
	v_mfma_f32_32x32x16_bf16 v[16:31], v[80:83], v[72:75], v[16:31]
	s_mov_b32 m0, s20
	v_lshl_add_u64 v[66:67], v[32:33], 0, s[52:53]
	s_mov_b64 s[26:27], 0x20200
	v_lshl_add_u64 v[72:73], v[32:33], 0, s[26:27]
	global_load_lds_dwordx4 v[66:67], off
	s_mov_b32 m0, s19
	s_nop 0
	global_load_lds_dwordx4 v[72:73], off
	v_mfma_f32_32x32x16_bf16 v[0:15], v[80:83], v[76:79], v[0:15]
	s_mov_b64 s[26:27], 0x40200
	v_lshl_add_u64 v[66:67], v[32:33], 0, s[26:27]
	s_mov_b32 m0, s18
	s_nop 0
	global_load_lds_dwordx4 v[66:67], off
	v_add_u32_e32 v67, v90, v86
	ds_read_b128 v[72:75], v67
	v_add_u32_e32 v66, v89, v86
	ds_read_b128 v[76:79], v66
	ds_read_b128 v[80:83], v66 offset:4096
	s_waitcnt lgkmcnt(0)
	v_mfma_f32_32x32x16_bf16 v[16:31], v[72:75], v[76:79], v[16:31]
	s_mov_b64 s[26:27], 0x60200
	v_lshl_add_u64 v[76:77], v[32:33], 0, s[26:27]
	s_mov_b32 m0, s13
	s_nop 0
	global_load_lds_dwordx4 v[76:77], off
	v_mfma_f32_32x32x16_bf16 v[0:15], v[72:75], v[80:83], v[0:15]
	s_mov_b32 m0, s12
	s_nop 0
	global_load_lds_dwordx4 v[84:85], off
	v_add_u32_e32 v64, v89, v87
	v_add_u32_e32 v72, v90, v87
	ds_read_b128 v[74:77], v64
	ds_read_b128 v[78:81], v64 offset:4096
	ds_read_b128 v[82:85], v72
	v_add_u32_e32 v73, v89, v88
	s_waitcnt lgkmcnt(0)
	v_mfma_f32_32x32x16_bf16 v[16:31], v[82:85], v[74:77], v[16:31]
	v_add_u32_e32 v74, v90, v88
	v_lshl_add_u64 v[88:89], v[34:35], 0, s[88:89]
	v_mfma_f32_32x32x16_bf16 v[0:15], v[82:85], v[78:81], v[0:15]
	ds_read_b128 v[76:79], v74
	ds_read_b128 v[80:83], v73 offset:4096
	ds_read_b128 v[84:87], v73
	s_waitcnt vmcnt(5)
	s_barrier
	s_waitcnt lgkmcnt(0)
	v_mfma_f32_32x32x16_bf16 v[16:31], v[76:79], v[84:87], v[16:31]
	v_mfma_f32_32x32x16_bf16 v[0:15], v[76:79], v[80:83], v[0:15]
	ds_read_b128 v[76:79], v37
	ds_read_b128 v[80:83], v37 offset:4096
	ds_read_b128 v[84:87], v36 offset:32768
	s_waitcnt lgkmcnt(0)
	v_mfma_f32_32x32x16_bf16 v[16:31], v[84:87], v[76:79], v[16:31]
	s_mov_b32 m0, s9
	v_lshl_add_u64 v[76:77], v[32:33], 0, s[88:89]
	s_mov_b64 s[26:27], 0x20280
	v_lshl_add_u64 v[78:79], v[32:33], 0, s[26:27]
	global_load_lds_dwordx4 v[76:77], off
	s_mov_b32 m0, s7
	s_nop 0
	global_load_lds_dwordx4 v[78:79], off
	v_mfma_f32_32x32x16_bf16 v[0:15], v[84:87], v[80:83], v[0:15]
	s_mov_b64 s[26:27], 0x40280
	v_lshl_add_u64 v[76:77], v[32:33], 0, s[26:27]
	s_mov_b32 m0, s8
	s_nop 0
	global_load_lds_dwordx4 v[76:77], off
	ds_read_b128 v[76:79], v39 offset:32768
	ds_read_b128 v[80:83], v38
	ds_read_b128 v[84:87], v38 offset:4096
	s_waitcnt lgkmcnt(0)
	v_mfma_f32_32x32x16_bf16 v[16:31], v[76:79], v[80:83], v[16:31]
	s_mov_b64 s[26:27], 0x60280
	v_lshl_add_u64 v[80:81], v[32:33], 0, s[26:27]
	s_mov_b32 m0, s10
	s_nop 0
	global_load_lds_dwordx4 v[80:81], off
	v_mfma_f32_32x32x16_bf16 v[0:15], v[76:79], v[84:87], v[0:15]
	s_mov_b32 m0, s11
	s_nop 0
	global_load_lds_dwordx4 v[88:89], off
	ds_read_b128 v[76:79], v40
	ds_read_b128 v[80:83], v40 offset:4096
	ds_read_b128 v[84:87], v41 offset:32768
	v_lshl_add_u64 v[88:89], v[34:35], 0, s[70:71]
	s_waitcnt lgkmcnt(0)
	v_mfma_f32_32x32x16_bf16 v[16:31], v[84:87], v[76:79], v[16:31]
	v_mfma_f32_32x32x16_bf16 v[0:15], v[84:87], v[80:83], v[0:15]
	ds_read_b128 v[76:79], v42 offset:32768
	ds_read_b128 v[80:83], v43 offset:4096
	ds_read_b128 v[84:87], v43
	s_waitcnt vmcnt(5)
	s_barrier
; #define MFMA(a, b, c) __builtin_amdgcn_mfma_f32_32x32x16_bf16((a), (b), (c), 0, 0, 0)
;     ...
;     const bool pre = (kt + DIST < nk);
;     const char* base = smem + (kt % NSTG) * STAGE;
;     const char* pa = base + (wrow_act + r) * 128;
;     const char* pw = base + ABYTES + (wrow_w + r) * 128;
;     constexpr int NM = NI * MJ;
;     constexpr int PPS = (NLD + 1) / 2;
; #pragma unroll
;     for (int s = 0; s < 4; ++s) {
;       bf16x8 af[MJ], wf[NI];
; #pragma unroll
;       for (int j = 0; j < MJ; ++j) af[j] = *(const bf16x8*)(pa + j * 32 * 128 + xo[s]);
; #pragma unroll
;       for (int i = 0; i < NI; ++i) wf[i] = *(const bf16x8*)(pw + i * 32 * 128 + xo[s]);
; #pragma unroll
;       for (int m = 0; m < NM; ++m) {
;         const int i = m / MJ, j = m % MJ;
;         acc[i][j] = MFMA(wf[i], af[j], acc[i][j]);
;         if (s < 2 && NM >= PPS) {
;           constexpr int EVERY = (NM / PPS) > 0 ? (NM / PPS) : 1;
;           if ((m + 1) % EVERY == 0) {
;             const int pc = s * PPS + (m + 1) / EVERY - 1;
;             if ((m + 1) / EVERY <= PPS && pc < NLD) {
;               __builtin_amdgcn_sched_barrier(0);
;               if (pre) issue_piece(kt + DIST, pc);
;               __builtin_amdgcn_sched_barrier(0);
;             }
;           }
;         }
;         if (s < 2 && NM < PPS) {
;           const int slot = s * NM + m;
;           __builtin_amdgcn_sched_barrier(0);
; #pragma unroll
;           for (int pc = 0; pc < NLD; ++pc)
;             if ((pc * 2 * NM) / NLD == slot && pre) issue_piece(kt + DIST, pc);
;           __builtin_amdgcn_sched_barrier(0);
;         }
;       }
;     }
	s_waitcnt lgkmcnt(0)
	v_mfma_f32_32x32x16_bf16 v[16:31], v[76:79], v[84:87], v[16:31]
	v_mfma_f32_32x32x16_bf16 v[0:15], v[76:79], v[80:83], v[0:15]
	ds_read_b128 v[76:79], v37 offset:49152
	ds_read_b128 v[80:83], v37 offset:53248
	ds_read_b128 v[84:87], v51
	s_waitcnt lgkmcnt(0)
	v_mfma_f32_32x32x16_bf16 v[16:31], v[84:87], v[76:79], v[16:31]
	s_mov_b32 m0, s25
	v_lshl_add_u64 v[76:77], v[32:33], 0, s[70:71]
	s_mov_b64 s[26:27], 0x20300
	v_lshl_add_u64 v[78:79], v[32:33], 0, s[26:27]
	global_load_lds_dwordx4 v[76:77], off
	s_mov_b32 m0, s24
	s_nop 0
	global_load_lds_dwordx4 v[78:79], off
	v_mfma_f32_32x32x16_bf16 v[0:15], v[84:87], v[80:83], v[0:15]
	s_mov_b64 s[26:27], 0x40300
	v_lshl_add_u64 v[76:77], v[32:33], 0, s[26:27]
	s_mov_b32 m0, s23
	s_nop 0
	global_load_lds_dwordx4 v[76:77], off
	ds_read_b128 v[76:79], v58
	ds_read_b128 v[80:83], v38 offset:49152
	ds_read_b128 v[84:87], v38 offset:53248
	s_waitcnt lgkmcnt(0)
	v_mfma_f32_32x32x16_bf16 v[16:31], v[76:79], v[80:83], v[16:31]
	s_mov_b64 s[26:27], 0x60300
	v_lshl_add_u64 v[80:81], v[32:33], 0, s[26:27]
	s_mov_b32 m0, s22
	s_nop 0
	global_load_lds_dwordx4 v[80:81], off
	v_mfma_f32_32x32x16_bf16 v[0:15], v[76:79], v[84:87], v[0:15]
	s_mov_b32 m0, s21
	s_nop 0
	global_load_lds_dwordx4 v[88:89], off
	ds_read_b128 v[76:79], v40 offset:49152
	ds_read_b128 v[80:83], v40 offset:53248
	ds_read_b128 v[84:87], v60
	v_lshl_add_u64 v[88:89], v[34:35], 0, s[36:37]
	s_waitcnt lgkmcnt(0)
	v_mfma_f32_32x32x16_bf16 v[16:31], v[84:87], v[76:79], v[16:31]
	v_mfma_f32_32x32x16_bf16 v[0:15], v[84:87], v[80:83], v[0:15]
	ds_read_b128 v[76:79], v61
	ds_read_b128 v[80:83], v43 offset:53248
	ds_read_b128 v[84:87], v43 offset:49152
	s_waitcnt vmcnt(5)
	s_barrier
	s_waitcnt lgkmcnt(0)
	v_mfma_f32_32x32x16_bf16 v[16:31], v[76:79], v[84:87], v[16:31]
	v_mfma_f32_32x32x16_bf16 v[0:15], v[76:79], v[80:83], v[0:15]
	ds_read_b128 v[76:79], v62
	ds_read_b128 v[80:83], v62 offset:4096
	ds_read_b128 v[84:87], v63
	s_waitcnt lgkmcnt(0)
	v_mfma_f32_32x32x16_bf16 v[16:31], v[84:87], v[76:79], v[16:31]
	s_mov_b32 m0, s20
	v_lshl_add_u64 v[76:77], v[32:33], 0, s[36:37]
	s_mov_b64 s[26:27], 0x20380
	v_lshl_add_u64 v[78:79], v[32:33], 0, s[26:27]
	global_load_lds_dwordx4 v[76:77], off
	s_mov_b32 m0, s19
	s_nop 0
	global_load_lds_dwordx4 v[78:79], off
	v_mfma_f32_32x32x16_bf16 v[0:15], v[84:87], v[80:83], v[0:15]
	s_mov_b64 s[26:27], 0x40380
	v_lshl_add_u64 v[76:77], v[32:33], 0, s[26:27]
	s_mov_b32 m0, s18
	s_nop 0
	global_load_lds_dwordx4 v[76:77], off
	ds_read_b128 v[76:79], v67
	ds_read_b128 v[80:83], v66
	ds_read_b128 v[84:87], v66 offset:4096
	s_waitcnt lgkmcnt(0)
	v_mfma_f32_32x32x16_bf16 v[16:31], v[76:79], v[80:83], v[16:31]
	s_mov_b64 s[26:27], 0x60380
	v_lshl_add_u64 v[80:81], v[32:33], 0, s[26:27]
	s_mov_b32 m0, s13
	s_nop 0
	global_load_lds_dwordx4 v[80:81], off
	v_mfma_f32_32x32x16_bf16 v[0:15], v[76:79], v[84:87], v[0:15]
	s_mov_b32 m0, s12
	s_nop 0
	global_load_lds_dwordx4 v[88:89], off
	ds_read_b128 v[76:79], v64
	ds_read_b128 v[80:83], v64 offset:4096
	ds_read_b128 v[84:87], v72
	v_lshl_add_u64 v[88:89], v[34:35], 0, s[54:55]
	s_waitcnt lgkmcnt(0)
	v_mfma_f32_32x32x16_bf16 v[16:31], v[84:87], v[76:79], v[16:31]
	v_mfma_f32_32x32x16_bf16 v[0:15], v[84:87], v[80:83], v[0:15]
	ds_read_b128 v[76:79], v74
	ds_read_b128 v[80:83], v73 offset:4096
	ds_read_b128 v[84:87], v73
	s_waitcnt vmcnt(5)
	s_barrier
	s_waitcnt lgkmcnt(0)
	v_mfma_f32_32x32x16_bf16 v[16:31], v[76:79], v[84:87], v[16:31]
	v_mfma_f32_32x32x16_bf16 v[0:15], v[76:79], v[80:83], v[0:15]
	ds_read_b128 v[76:79], v37
	ds_read_b128 v[80:83], v37 offset:4096
	ds_read_b128 v[84:87], v36 offset:32768
	s_waitcnt lgkmcnt(0)
	v_mfma_f32_32x32x16_bf16 v[16:31], v[84:87], v[76:79], v[16:31]
	s_mov_b32 m0, s9
	v_lshl_add_u64 v[76:77], v[32:33], 0, s[54:55]
	s_mov_b64 s[26:27], 0x20400
	v_lshl_add_u64 v[78:79], v[32:33], 0, s[26:27]
	global_load_lds_dwordx4 v[76:77], off
	s_mov_b32 m0, s7
	s_nop 0
	global_load_lds_dwordx4 v[78:79], off
	v_mfma_f32_32x32x16_bf16 v[0:15], v[84:87], v[80:83], v[0:15]
	s_mov_b64 s[26:27], 0x40400
	v_lshl_add_u64 v[76:77], v[32:33], 0, s[26:27]
	s_mov_b32 m0, s8
	s_nop 0
	global_load_lds_dwordx4 v[76:77], off
	ds_read_b128 v[76:79], v39 offset:32768
	ds_read_b128 v[80:83], v38
	ds_read_b128 v[84:87], v38 offset:4096
	s_waitcnt lgkmcnt(0)
	v_mfma_f32_32x32x16_bf16 v[16:31], v[76:79], v[80:83], v[16:31]
	s_mov_b64 s[26:27], 0x60400
	v_lshl_add_u64 v[80:81], v[32:33], 0, s[26:27]
	s_mov_b32 m0, s10
	s_nop 0
	global_load_lds_dwordx4 v[80:81], off
	v_mfma_f32_32x32x16_bf16 v[0:15], v[76:79], v[84:87], v[0:15]
	s_mov_b32 m0, s11
	s_nop 0
	global_load_lds_dwordx4 v[88:89], off
	ds_read_b128 v[76:79], v40
	ds_read_b128 v[80:83], v40 offset:4096
	ds_read_b128 v[84:87], v41 offset:32768
	v_lshl_add_u64 v[88:89], v[34:35], 0, s[96:97]
	s_waitcnt lgkmcnt(0)
	v_mfma_f32_32x32x16_bf16 v[16:31], v[84:87], v[76:79], v[16:31]
	v_mfma_f32_32x32x16_bf16 v[0:15], v[84:87], v[80:83], v[0:15]
	ds_read_b128 v[76:79], v42 offset:32768
	ds_read_b128 v[80:83], v43 offset:4096
	ds_read_b128 v[84:87], v43
	s_waitcnt vmcnt(5)
	s_barrier
; #define MFMA(a, b, c) __builtin_amdgcn_mfma_f32_32x32x16_bf16((a), (b), (c), 0, 0, 0)
;     ...
;     const bool pre = (kt + DIST < nk);
;     const char* base = smem + (kt % NSTG) * STAGE;
;     const char* pa = base + (wrow_act + r) * 128;
;     const char* pw = base + ABYTES + (wrow_w + r) * 128;
;     constexpr int NM = NI * MJ;
;     constexpr int PPS = (NLD + 1) / 2;
; #pragma unroll
;     for (int s = 0; s < 4; ++s) {
;       bf16x8 af[MJ], wf[NI];
; #pragma unroll
;       for (int j = 0; j < MJ; ++j) af[j] = *(const bf16x8*)(pa + j * 32 * 128 + xo[s]);
; #pragma unroll
;       for (int i = 0; i < NI; ++i) wf[i] = *(const bf16x8*)(pw + i * 32 * 128 + xo[s]);
; #pragma unroll
;       for (int m = 0; m < NM; ++m) {
;         const int i = m / MJ, j = m % MJ;
;         acc[i][j] = MFMA(wf[i], af[j], acc[i][j]);
;         if (s < 2 && NM >= PPS) {
;           constexpr int EVERY = (NM / PPS) > 0 ? (NM / PPS) : 1;
;           if ((m + 1) % EVERY == 0) {
;             const int pc = s * PPS + (m + 1) / EVERY - 1;
;             if ((m + 1) / EVERY <= PPS && pc < NLD) {
;               __builtin_amdgcn_sched_barrier(0);
;               if (pre) issue_piece(kt + DIST, pc);
;               __builtin_amdgcn_sched_barrier(0);
;             }
;           }
;         }
;         if (s < 2 && NM < PPS) {
;           const int slot = s * NM + m;
;           __builtin_amdgcn_sched_barrier(0);
; #pragma unroll
;           for (int pc = 0; pc < NLD; ++pc)
;             if ((pc * 2 * NM) / NLD == slot && pre) issue_piece(kt + DIST, pc);
;           __builtin_amdgcn_sched_barrier(0);
;         }
;       }
;     }
	s_waitcnt lgkmcnt(0)
	v_mfma_f32_32x32x16_bf16 v[16:31], v[76:79], v[84:87], v[16:31]
	v_mfma_f32_32x32x16_bf16 v[0:15], v[76:79], v[80:83], v[0:15]
	ds_read_b128 v[76:79], v37 offset:49152
	ds_read_b128 v[80:83], v37 offset:53248
	ds_read_b128 v[84:87], v51
	s_waitcnt lgkmcnt(0)
	v_mfma_f32_32x32x16_bf16 v[16:31], v[84:87], v[76:79], v[16:31]
	s_mov_b32 m0, s25
	v_lshl_add_u64 v[76:77], v[32:33], 0, s[96:97]
	s_mov_b64 s[26:27], 0x20480
	v_lshl_add_u64 v[78:79], v[32:33], 0, s[26:27]
	global_load_lds_dwordx4 v[76:77], off
	s_mov_b32 m0, s24
	s_nop 0
	global_load_lds_dwordx4 v[78:79], off
	v_mfma_f32_32x32x16_bf16 v[0:15], v[84:87], v[80:83], v[0:15]
	s_mov_b64 s[24:25], 0x40480
	v_lshl_add_u64 v[76:77], v[32:33], 0, s[24:25]
	s_mov_b32 m0, s23
	s_nop 0
	global_load_lds_dwordx4 v[76:77], off
	ds_read_b128 v[76:79], v58
	ds_read_b128 v[80:83], v38 offset:49152
	ds_read_b128 v[84:87], v38 offset:53248
	s_waitcnt lgkmcnt(0)
	v_mfma_f32_32x32x16_bf16 v[16:31], v[76:79], v[80:83], v[16:31]
	s_mov_b64 s[24:25], 0x60480
	v_lshl_add_u64 v[80:81], v[32:33], 0, s[24:25]
	s_mov_b32 m0, s22
	s_nop 0
	global_load_lds_dwordx4 v[80:81], off
	v_mfma_f32_32x32x16_bf16 v[0:15], v[76:79], v[84:87], v[0:15]
	s_mov_b32 m0, s21
	s_nop 0
	global_load_lds_dwordx4 v[88:89], off
	ds_read_b128 v[76:79], v40 offset:49152
	ds_read_b128 v[80:83], v40 offset:53248
	ds_read_b128 v[84:87], v60
	v_lshl_add_u64 v[88:89], v[34:35], 0, s[30:31]
	s_waitcnt lgkmcnt(0)
	v_mfma_f32_32x32x16_bf16 v[16:31], v[84:87], v[76:79], v[16:31]
	v_mfma_f32_32x32x16_bf16 v[0:15], v[84:87], v[80:83], v[0:15]
	ds_read_b128 v[76:79], v61
	ds_read_b128 v[80:83], v43 offset:53248
	ds_read_b128 v[84:87], v43 offset:49152
	s_waitcnt vmcnt(5)
	s_barrier
	s_waitcnt lgkmcnt(0)
	v_mfma_f32_32x32x16_bf16 v[16:31], v[76:79], v[84:87], v[16:31]
	v_mfma_f32_32x32x16_bf16 v[0:15], v[76:79], v[80:83], v[0:15]
	ds_read_b128 v[76:79], v62
	ds_read_b128 v[80:83], v62 offset:4096
	ds_read_b128 v[84:87], v63
	s_waitcnt lgkmcnt(0)
	v_mfma_f32_32x32x16_bf16 v[16:31], v[84:87], v[76:79], v[16:31]
	s_mov_b32 m0, s20
	v_lshl_add_u64 v[76:77], v[32:33], 0, s[30:31]
	s_mov_b64 s[20:21], 0x20500
	v_lshl_add_u64 v[78:79], v[32:33], 0, s[20:21]
	global_load_lds_dwordx4 v[76:77], off
	s_mov_b32 m0, s19
	s_nop 0
	global_load_lds_dwordx4 v[78:79], off
	v_mfma_f32_32x32x16_bf16 v[0:15], v[84:87], v[80:83], v[0:15]
	s_mov_b64 s[20:21], 0x40500
	v_lshl_add_u64 v[76:77], v[32:33], 0, s[20:21]
	s_mov_b32 m0, s18
	s_nop 0
	global_load_lds_dwordx4 v[76:77], off
	ds_read_b128 v[76:79], v67
	ds_read_b128 v[80:83], v66
	ds_read_b128 v[84:87], v66 offset:4096
	s_waitcnt lgkmcnt(0)
	v_mfma_f32_32x32x16_bf16 v[16:31], v[76:79], v[80:83], v[16:31]
	s_mov_b64 s[18:19], 0x60500
	v_lshl_add_u64 v[80:81], v[32:33], 0, s[18:19]
	s_mov_b32 m0, s13
	s_nop 0
	global_load_lds_dwordx4 v[80:81], off
	v_mfma_f32_32x32x16_bf16 v[0:15], v[76:79], v[84:87], v[0:15]
	s_mov_b32 m0, s12
	s_nop 0
	global_load_lds_dwordx4 v[88:89], off
	ds_read_b128 v[76:79], v64
	ds_read_b128 v[80:83], v64 offset:4096
	ds_read_b128 v[84:87], v72
	v_lshl_add_u64 v[88:89], v[34:35], 0, s[84:85]
	s_waitcnt lgkmcnt(0)
	v_mfma_f32_32x32x16_bf16 v[16:31], v[84:87], v[76:79], v[16:31]
	v_mfma_f32_32x32x16_bf16 v[0:15], v[84:87], v[80:83], v[0:15]
	ds_read_b128 v[76:79], v74
	ds_read_b128 v[80:83], v73 offset:4096
	ds_read_b128 v[84:87], v73
	s_waitcnt vmcnt(5)
	s_barrier
	s_waitcnt lgkmcnt(0)
	v_mfma_f32_32x32x16_bf16 v[16:31], v[76:79], v[84:87], v[16:31]
	v_mfma_f32_32x32x16_bf16 v[0:15], v[76:79], v[80:83], v[0:15]
	ds_read_b128 v[76:79], v37
	ds_read_b128 v[80:83], v37 offset:4096
	ds_read_b128 v[84:87], v36 offset:32768
	s_waitcnt lgkmcnt(0)
	v_mfma_f32_32x32x16_bf16 v[16:31], v[84:87], v[76:79], v[16:31]
	s_mov_b32 m0, s9
	v_lshl_add_u64 v[76:77], v[32:33], 0, s[84:85]
	s_mov_b64 s[12:13], 0x20580
	v_lshl_add_u64 v[78:79], v[32:33], 0, s[12:13]
	global_load_lds_dwordx4 v[76:77], off
	s_mov_b32 m0, s7
	s_nop 0
	global_load_lds_dwordx4 v[78:79], off
	v_mfma_f32_32x32x16_bf16 v[0:15], v[84:87], v[80:83], v[0:15]
	s_mov_b64 s[12:13], 0x40580
	v_lshl_add_u64 v[76:77], v[32:33], 0, s[12:13]
	s_mov_b32 m0, s8
	s_nop 0
	global_load_lds_dwordx4 v[76:77], off
	ds_read_b128 v[76:79], v39 offset:32768
	ds_read_b128 v[80:83], v38
	ds_read_b128 v[84:87], v38 offset:4096
	s_waitcnt lgkmcnt(0)
	v_mfma_f32_32x32x16_bf16 v[16:31], v[76:79], v[80:83], v[16:31]
	s_mov_b64 s[8:9], 0x60580
	v_lshl_add_u64 v[80:81], v[32:33], 0, s[8:9]
	s_mov_b32 m0, s10
	s_nop 0
	global_load_lds_dwordx4 v[80:81], off
	v_mfma_f32_32x32x16_bf16 v[0:15], v[76:79], v[84:87], v[0:15]
	s_mov_b32 m0, s11
	s_nop 0
	global_load_lds_dwordx4 v[88:89], off
	ds_read_b128 v[76:79], v40
	ds_read_b128 v[80:83], v40 offset:4096
	ds_read_b128 v[84:87], v41 offset:32768
	v_lshl_add_u64 v[88:89], v[34:35], 0, s[38:39]
	s_waitcnt lgkmcnt(0)
	v_mfma_f32_32x32x16_bf16 v[16:31], v[84:87], v[76:79], v[16:31]
	v_mfma_f32_32x32x16_bf16 v[0:15], v[84:87], v[80:83], v[0:15]
	ds_read_b128 v[76:79], v42 offset:32768
	ds_read_b128 v[80:83], v43 offset:4096
	ds_read_b128 v[84:87], v43
	s_waitcnt vmcnt(5)
	s_barrier
; #define MFMA(a, b, c) __builtin_amdgcn_mfma_f32_32x32x16_bf16((a), (b), (c), 0, 0, 0)
;     ...
;     const bool pre = (kt + DIST < nk);
;     const char* base = smem + (kt % NSTG) * STAGE;
;     const char* pa = base + (wrow_act + r) * 128;
;     const char* pw = base + ABYTES + (wrow_w + r) * 128;
;     constexpr int NM = NI * MJ;
;     constexpr int PPS = (NLD + 1) / 2;
; #pragma unroll
;     for (int s = 0; s < 4; ++s) {
;       bf16x8 af[MJ], wf[NI];
; #pragma unroll
;       for (int j = 0; j < MJ; ++j) af[j] = *(const bf16x8*)(pa + j * 32 * 128 + xo[s]);
; #pragma unroll
;       for (int i = 0; i < NI; ++i) wf[i] = *(const bf16x8*)(pw + i * 32 * 128 + xo[s]);
; #pragma unroll
;       for (int m = 0; m < NM; ++m) {
;         const int i = m / MJ, j = m % MJ;
;         acc[i][j] = MFMA(wf[i], af[j], acc[i][j]);
;         if (s < 2 && NM >= PPS) {
;           constexpr int EVERY = (NM / PPS) > 0 ? (NM / PPS) : 1;
;           if ((m + 1) % EVERY == 0) {
;             const int pc = s * PPS + (m + 1) / EVERY - 1;
;             if ((m + 1) / EVERY <= PPS && pc < NLD) {
;               __builtin_amdgcn_sched_barrier(0);
;               if (pre) issue_piece(kt + DIST, pc);
;               __builtin_amdgcn_sched_barrier(0);
;             }
;           }
;         }
;         if (s < 2 && NM < PPS) {
;           const int slot = s * NM + m;
;           __builtin_amdgcn_sched_barrier(0);
; #pragma unroll
;           for (int pc = 0; pc < NLD; ++pc)
;             if ((pc * 2 * NM) / NLD == slot && pre) issue_piece(kt + DIST, pc);
;           __builtin_amdgcn_sched_barrier(0);
;         }
;       }
;     }
	s_waitcnt lgkmcnt(0)
	v_mfma_f32_32x32x16_bf16 v[16:31], v[76:79], v[84:87], v[16:31]
	v_mfma_f32_32x32x16_bf16 v[0:15], v[76:79], v[80:83], v[0:15]
	ds_read_b128 v[76:79], v37 offset:49152
	ds_read_b128 v[80:83], v37 offset:53248
	ds_read_b128 v[84:87], v51
	s_waitcnt lgkmcnt(0)
	v_mfma_f32_32x32x16_bf16 v[16:31], v[84:87], v[76:79], v[16:31]
	v_readfirstlane_b32 s10, v70
	v_lshl_add_u64 v[76:77], v[32:33], 0, s[38:39]
	s_mov_b64 s[8:9], 0x20600
	s_mov_b32 m0, s10
	v_readfirstlane_b32 s7, v71
	v_lshl_add_u64 v[78:79], v[32:33], 0, s[8:9]
	global_load_lds_dwordx4 v[76:77], off
	s_mov_b32 m0, s7
	s_nop 0
	global_load_lds_dwordx4 v[78:79], off
	v_mfma_f32_32x32x16_bf16 v[0:15], v[84:87], v[80:83], v[0:15]
	s_mov_b64 s[8:9], 0x40600
	v_lshl_add_u64 v[70:71], v[32:33], 0, s[8:9]
	v_readfirstlane_b32 s8, v69
	s_mov_b32 m0, s8
	s_nop 0
	global_load_lds_dwordx4 v[70:71], off
	ds_read_b128 v[76:79], v58
	ds_read_b128 v[80:83], v38 offset:49152
	ds_read_b128 v[84:87], v38 offset:53248
	s_waitcnt lgkmcnt(0)
	v_mfma_f32_32x32x16_bf16 v[16:31], v[76:79], v[80:83], v[16:31]
	s_mov_b64 s[12:13], 0x60600
	v_readfirstlane_b32 s9, v68
	v_lshl_add_u64 v[70:71], v[32:33], 0, s[12:13]
	s_mov_b32 m0, s9
	s_nop 0
	global_load_lds_dwordx4 v[70:71], off
	v_mfma_f32_32x32x16_bf16 v[0:15], v[76:79], v[84:87], v[0:15]
	v_readfirstlane_b32 s11, v65
	s_mov_b32 m0, s11
	s_nop 0
	global_load_lds_dwordx4 v[88:89], off
	ds_read_b128 v[68:71], v40 offset:49152
	ds_read_b128 v[76:79], v40 offset:53248
	ds_read_b128 v[80:83], v60
	v_lshl_add_u64 v[84:85], v[34:35], 0, s[68:69]
	s_waitcnt lgkmcnt(0)
	v_mfma_f32_32x32x16_bf16 v[16:31], v[80:83], v[68:71], v[16:31]
	v_mfma_f32_32x32x16_bf16 v[0:15], v[80:83], v[76:79], v[0:15]
	ds_read_b128 v[68:71], v61
	ds_read_b128 v[76:79], v43 offset:53248
	ds_read_b128 v[80:83], v43 offset:49152
	s_waitcnt vmcnt(5)
	s_barrier
	s_waitcnt lgkmcnt(0)
	v_mfma_f32_32x32x16_bf16 v[16:31], v[68:71], v[80:83], v[16:31]
	v_mfma_f32_32x32x16_bf16 v[0:15], v[68:71], v[76:79], v[0:15]
	ds_read_b128 v[68:71], v62
	ds_read_b128 v[76:79], v62 offset:4096
	ds_read_b128 v[80:83], v63
	s_waitcnt lgkmcnt(0)
	v_mfma_f32_32x32x16_bf16 v[16:31], v[80:83], v[68:71], v[16:31]
	s_mov_b64 s[12:13], 0x20680
	v_lshl_add_u64 v[70:71], v[32:33], 0, s[12:13]
	v_readfirstlane_b32 s12, v56
	v_lshl_add_u64 v[68:69], v[32:33], 0, s[68:69]
	s_mov_b32 m0, s12
	v_readfirstlane_b32 s12, v59
	global_load_lds_dwordx4 v[68:69], off
	s_mov_b32 m0, s12
	s_nop 0
	global_load_lds_dwordx4 v[70:71], off
	v_mfma_f32_32x32x16_bf16 v[0:15], v[80:83], v[76:79], v[0:15]
	s_mov_b64 s[12:13], 0x40680
	v_lshl_add_u64 v[68:69], v[32:33], 0, s[12:13]
	v_readfirstlane_b32 s12, v57
	s_mov_b32 m0, s12
	s_nop 0
	global_load_lds_dwordx4 v[68:69], off
	ds_read_b128 v[68:71], v67
	ds_read_b128 v[76:79], v66
	ds_read_b128 v[80:83], v66 offset:4096
	s_waitcnt lgkmcnt(0)
	v_mfma_f32_32x32x16_bf16 v[16:31], v[68:71], v[76:79], v[16:31]
	v_readfirstlane_b32 s12, v50
	v_lshl_add_u64 v[56:57], v[32:33], 0, s[58:59]
	s_mov_b32 m0, s12
	s_nop 0
	global_load_lds_dwordx4 v[56:57], off
	v_mfma_f32_32x32x16_bf16 v[0:15], v[68:71], v[80:83], v[0:15]
	v_readfirstlane_b32 s12, v49
	s_mov_b32 m0, s12
	s_nop 0
	global_load_lds_dwordx4 v[84:85], off
	ds_read_b128 v[68:71], v64
	ds_read_b128 v[76:79], v64 offset:4096
	ds_read_b128 v[80:83], v72
	v_lshl_add_u64 v[56:57], v[34:35], 0, s[60:61]
	s_waitcnt lgkmcnt(0)
	v_mfma_f32_32x32x16_bf16 v[16:31], v[80:83], v[68:71], v[16:31]
	v_mfma_f32_32x32x16_bf16 v[0:15], v[80:83], v[76:79], v[0:15]
	ds_read_b128 v[68:71], v74
	ds_read_b128 v[76:79], v73 offset:4096
	ds_read_b128 v[80:83], v73
	s_waitcnt vmcnt(5)
	s_barrier
	s_waitcnt lgkmcnt(0)
	v_mfma_f32_32x32x16_bf16 v[16:31], v[68:71], v[80:83], v[16:31]
	v_mfma_f32_32x32x16_bf16 v[0:15], v[68:71], v[76:79], v[0:15]
	ds_read_b128 v[68:71], v37
	ds_read_b128 v[76:79], v37 offset:4096
	ds_read_b128 v[80:83], v36 offset:32768
	s_waitcnt lgkmcnt(0)
	v_mfma_f32_32x32x16_bf16 v[16:31], v[80:83], v[68:71], v[16:31]
	v_readfirstlane_b32 s12, v44
	v_lshl_add_u64 v[68:69], v[32:33], 0, s[60:61]
	s_mov_b32 m0, s12
	v_readfirstlane_b32 s12, v45
	v_lshl_add_u64 v[70:71], v[32:33], 0, s[90:91]
	global_load_lds_dwordx4 v[68:69], off
	s_mov_b32 m0, s12
	s_nop 0
	global_load_lds_dwordx4 v[70:71], off
	v_mfma_f32_32x32x16_bf16 v[0:15], v[80:83], v[76:79], v[0:15]
	v_readfirstlane_b32 s12, v46
	v_lshl_add_u64 v[44:45], v[32:33], 0, vcc
	s_mov_b32 m0, s12
	s_nop 0
	global_load_lds_dwordx4 v[44:45], off
	ds_read_b128 v[68:71], v39 offset:32768
	ds_read_b128 v[76:79], v38
	ds_read_b128 v[80:83], v38 offset:4096
	s_waitcnt lgkmcnt(0)
	v_mfma_f32_32x32x16_bf16 v[16:31], v[68:71], v[76:79], v[16:31]
	v_readfirstlane_b32 s12, v47
	v_lshl_add_u64 v[44:45], v[32:33], 0, s[28:29]
	s_mov_b32 m0, s12
	s_nop 0
	global_load_lds_dwordx4 v[44:45], off
	v_mfma_f32_32x32x16_bf16 v[0:15], v[68:71], v[80:83], v[0:15]
	v_readfirstlane_b32 s12, v48
	s_mov_b32 m0, s12
	s_nop 0
	global_load_lds_dwordx4 v[56:57], off
	ds_read_b128 v[44:47], v41 offset:32768
	ds_read_b128 v[68:71], v40
	v_lshl_add_u64 v[34:35], v[34:35], 0, s[46:47]
	s_waitcnt lgkmcnt(0)
	v_mfma_f32_32x32x16_bf16 v[16:31], v[44:47], v[68:71], v[16:31]
	ds_read_b128 v[68:71], v40 offset:4096
	s_waitcnt lgkmcnt(0)
	v_mfma_f32_32x32x16_bf16 v[0:15], v[44:47], v[68:71], v[0:15]
	ds_read_b128 v[44:47], v42 offset:32768
	ds_read_b128 v[68:71], v43
	s_waitcnt lgkmcnt(0)
	v_mfma_f32_32x32x16_bf16 v[16:31], v[44:47], v[68:71], v[16:31]
	ds_read_b128 v[68:71], v43 offset:4096
	s_waitcnt vmcnt(5)
	s_barrier
; #define MFMA(a, b, c) __builtin_amdgcn_mfma_f32_32x32x16_bf16((a), (b), (c), 0, 0, 0)
;     ...
;     const bool pre = (kt + DIST < nk);
;     const char* base = smem + (kt % NSTG) * STAGE;
;     const char* pa = base + (wrow_act + r) * 128;
;     const char* pw = base + ABYTES + (wrow_w + r) * 128;
;     constexpr int NM = NI * MJ;
;     constexpr int PPS = (NLD + 1) / 2;
; #pragma unroll
;     for (int s = 0; s < 4; ++s) {
;       bf16x8 af[MJ], wf[NI];
; #pragma unroll
;       for (int j = 0; j < MJ; ++j) af[j] = *(const bf16x8*)(pa + j * 32 * 128 + xo[s]);
; #pragma unroll
;       for (int i = 0; i < NI; ++i) wf[i] = *(const bf16x8*)(pw + i * 32 * 128 + xo[s]);
; #pragma unroll
;       for (int m = 0; m < NM; ++m) {
;         const int i = m / MJ, j = m % MJ;
;         acc[i][j] = MFMA(wf[i], af[j], acc[i][j]);
;         if (s < 2 && NM >= PPS) {
;           constexpr int EVERY = (NM / PPS) > 0 ? (NM / PPS) : 1;
;           if ((m + 1) % EVERY == 0) {
;             const int pc = s * PPS + (m + 1) / EVERY - 1;
;             if ((m + 1) / EVERY <= PPS && pc < NLD) {
;               __builtin_amdgcn_sched_barrier(0);
;               if (pre) issue_piece(kt + DIST, pc);
;               __builtin_amdgcn_sched_barrier(0);
;             }
;           }
;         }
;         if (s < 2 && NM < PPS) {
;           const int slot = s * NM + m;
;           __builtin_amdgcn_sched_barrier(0);
; #pragma unroll
;           for (int pc = 0; pc < NLD; ++pc)
;             if ((pc * 2 * NM) / NLD == slot && pre) issue_piece(kt + DIST, pc);
;           __builtin_amdgcn_sched_barrier(0);
;         }
;       }
;     }
;   }
;   __builtin_amdgcn_s_barrier();
	s_waitcnt lgkmcnt(0)
	v_mfma_f32_32x32x16_bf16 v[0:15], v[44:47], v[68:71], v[0:15]
	ds_read_b128 v[44:47], v51
	ds_read_b128 v[48:51], v37 offset:49152
	ds_read_b128 v[68:71], v37 offset:53248
	s_waitcnt lgkmcnt(0)
	v_mfma_f32_32x32x16_bf16 v[16:31], v[44:47], v[48:51], v[16:31]
	s_mov_b32 m0, s10
	v_lshl_add_u64 v[48:49], v[32:33], 0, s[46:47]
	v_lshl_add_u64 v[50:51], v[32:33], 0, s[48:49]
	global_load_lds_dwordx4 v[48:49], off
	s_mov_b32 m0, s7
	s_nop 0
	global_load_lds_dwordx4 v[50:51], off
	v_mfma_f32_32x32x16_bf16 v[0:15], v[44:47], v[68:71], v[0:15]
	v_lshl_add_u64 v[44:45], v[32:33], 0, s[50:51]
	s_mov_b32 m0, s8
	s_nop 0
	global_load_lds_dwordx4 v[44:45], off
	ds_read_b128 v[44:47], v58
	ds_read_b128 v[48:51], v38 offset:49152
	ds_read_b128 v[56:59], v38 offset:53248
	s_waitcnt lgkmcnt(0)
	v_mfma_f32_32x32x16_bf16 v[16:31], v[44:47], v[48:51], v[16:31]
	v_lshl_add_u64 v[32:33], v[32:33], 0, s[86:87]
	s_mov_b32 m0, s9
	s_nop 0
	global_load_lds_dwordx4 v[32:33], off
	v_mfma_f32_32x32x16_bf16 v[0:15], v[44:47], v[56:59], v[0:15]
	s_mov_b32 m0, s11
	s_nop 0
	global_load_lds_dwordx4 v[34:35], off
	ds_read_b128 v[32:35], v60
	ds_read_b128 v[44:47], v40 offset:49152
	s_waitcnt lgkmcnt(0)
	v_mfma_f32_32x32x16_bf16 v[16:31], v[32:35], v[44:47], v[16:31]
	ds_read_b128 v[44:47], v40 offset:53248
	s_waitcnt lgkmcnt(0)
	v_mfma_f32_32x32x16_bf16 v[0:15], v[32:35], v[44:47], v[0:15]
	ds_read_b128 v[32:35], v61
	ds_read_b128 v[44:47], v43 offset:49152
	s_waitcnt lgkmcnt(0)
	v_mfma_f32_32x32x16_bf16 v[16:31], v[32:35], v[44:47], v[16:31]
	ds_read_b128 v[44:47], v43 offset:53248
	s_waitcnt vmcnt(5)
	s_barrier
	s_waitcnt lgkmcnt(0)
	v_mfma_f32_32x32x16_bf16 v[0:15], v[32:35], v[44:47], v[0:15]
	ds_read_b128 v[32:35], v63
	ds_read_b128 v[44:47], v62
	ds_read_b128 v[48:51], v62 offset:4096
	s_waitcnt lgkmcnt(0)
	v_mfma_f32_32x32x16_bf16 v[16:31], v[32:35], v[44:47], v[16:31]
	v_mfma_f32_32x32x16_bf16 v[0:15], v[32:35], v[48:51], v[0:15]
	ds_read_b128 v[32:35], v67
	ds_read_b128 v[44:47], v66
	ds_read_b128 v[48:51], v66 offset:4096
	s_waitcnt lgkmcnt(0)
	v_mfma_f32_32x32x16_bf16 v[16:31], v[32:35], v[44:47], v[16:31]
	v_mfma_f32_32x32x16_bf16 v[0:15], v[32:35], v[48:51], v[0:15]
	ds_read_b128 v[32:35], v72
	ds_read_b128 v[44:47], v64
	s_waitcnt lgkmcnt(0)
	v_mfma_f32_32x32x16_bf16 v[16:31], v[32:35], v[44:47], v[16:31]
	ds_read_b128 v[44:47], v64 offset:4096
	s_waitcnt lgkmcnt(0)
	v_mfma_f32_32x32x16_bf16 v[0:15], v[32:35], v[44:47], v[0:15]
	ds_read_b128 v[32:35], v74
	ds_read_b128 v[44:47], v73
	s_waitcnt lgkmcnt(0)
	v_mfma_f32_32x32x16_bf16 v[16:31], v[32:35], v[44:47], v[16:31]
	ds_read_b128 v[44:47], v73 offset:4096
	s_waitcnt vmcnt(0)
	s_barrier
	s_waitcnt lgkmcnt(0)
	v_mfma_f32_32x32x16_bf16 v[0:15], v[32:35], v[44:47], v[0:15]
	ds_read_b128 v[32:35], v36 offset:32768
	ds_read_b128 v[44:47], v37
	ds_read_b128 v[48:51], v37 offset:4096
	s_waitcnt lgkmcnt(0)
	v_mfma_f32_32x32x16_bf16 v[16:31], v[32:35], v[44:47], v[16:31]
	v_mfma_f32_32x32x16_bf16 v[0:15], v[32:35], v[48:51], v[0:15]
	ds_read_b128 v[32:35], v39 offset:32768
	ds_read_b128 v[44:47], v38
	ds_read_b128 v[36:39], v38 offset:4096
	s_waitcnt lgkmcnt(0)
	v_mfma_f32_32x32x16_bf16 v[16:31], v[32:35], v[44:47], v[16:31]
	v_mfma_f32_32x32x16_bf16 v[0:15], v[32:35], v[36:39], v[0:15]
	ds_read_b128 v[32:35], v40
	ds_read_b128 v[36:39], v40 offset:4096
	ds_read_b128 v[44:47], v41 offset:32768
	s_mulk_i32 s6, 0x2100
	v_lshl_or_b32 v144, s5, 8, v55
	v_lshl_add_u64 v[56:57], s[0:1], 0, v[144:145]
	s_add_i32 s3, s3, s2
	s_waitcnt lgkmcnt(0)
	v_mfma_f32_32x32x16_bf16 v[0:15], v[44:47], v[36:39], v[0:15]
	s_cmp_lt_i32 s3, 32
	v_mfma_f32_32x32x16_bf16 v[16:31], v[44:47], v[32:35], v[16:31]
	ds_read_b128 v[32:35], v42 offset:32768
	ds_read_b128 v[36:39], v43 offset:4096
	ds_read_b128 v[40:43], v43
	s_barrier
; DEV void phase_outproj(const Params& p, int l, int hf, char* smem) {
;     ...
;       const float* gate = mod + 4 * 3072 + 2048;
; #pragma unroll
;       for (int j = 0; j < 2; ++j) {
;         const int m = mt * 256 + wm * 64 + 32 * j + r;
;         const int bl = m / TP, tp = m - bl * TP;
;         float* dst = (float*)(ws + OFF_CTX1) + ((size_t)(hf * 2 + bl) * CTXL + tp) * DM;
; #pragma unroll
;         for (int g4 = 0; g4 < 4; ++g4) {
;           const int n = nt64 * 64 + wn * 32 + 8 * g4 + 4 * h;
;           const float4 xv = *(const float4*)(p.ctx + ((size_t)(hf * 2 + bl) * CTXL + tp) * DM + n);
;           const float4 gv = *(const float4*)(gate + n);
;           float4 o;
;           o.x = xv.x + gv.x * acc[0][j][4 * g4];
;           o.y = xv.y + gv.y * acc[0][j][4 * g4 + 1];
;           o.z = xv.z + gv.z * acc[0][j][4 * g4 + 2];
;           o.w = xv.w + gv.w * acc[0][j][4 * g4 + 3];
;           *(float4*)(dst + n) = o;
;         }
;       }
	s_waitcnt lgkmcnt(0)
	v_mfma_f32_32x32x16_bf16 v[0:15], v[32:35], v[36:39], v[0:15]
	v_add_u32_e32 v38, s6, v54
	v_mfma_f32_32x32x16_bf16 v[16:31], v[32:35], v[40:43], v[16:31]
	v_mul_hi_i32 v32, v38, s72
	v_lshrrev_b32_e32 v33, 31, v32
	v_ashrrev_i32_e32 v32, 11, v32
	v_add_u32_e32 v33, v32, v33
	v_add_u32_e32 v34, s4, v33
	v_mad_i32_i24 v32, v33, s73, v38
	v_ashrrev_i32_e32 v35, 31, v34
	v_ashrrev_i32_e32 v33, 31, v32
	v_lshlrev_b64 v[34:35], 20, v[34:35]
	v_lshl_add_u64 v[36:37], s[40:41], 0, v[34:35]
	v_lshlrev_b64 v[32:33], 12, v[32:33]
	v_lshl_add_u64 v[34:35], s[44:45], 0, v[34:35]
	v_lshl_add_u64 v[36:37], v[36:37], 0, v[32:33]
	v_lshl_add_u64 v[32:33], v[34:35], 0, v[32:33]
	v_or_b32_e32 v34, 32, v38
	v_mul_hi_i32 v35, v34, s72
	v_lshrrev_b32_e32 v38, 31, v35
	v_ashrrev_i32_e32 v35, 11, v35
	v_add_u32_e32 v35, v35, v38
	v_add_u32_e32 v38, s4, v35
	v_lshl_add_u64 v[50:51], v[32:33], 0, v[144:145]
	v_or_b32_e32 v32, 32, v144
	v_mov_b32_e32 v33, v145
	v_mad_i32_i24 v34, v35, s73, v34
	v_ashrrev_i32_e32 v39, 31, v38
	v_lshl_add_u64 v[40:41], s[0:1], 0, v[32:33]
	v_or_b32_e32 v32, 64, v144
	v_ashrrev_i32_e32 v35, 31, v34
	v_lshlrev_b64 v[38:39], 20, v[38:39]
	v_lshl_add_u64 v[48:49], v[36:37], 0, v[144:145]
	v_lshl_add_u64 v[36:37], s[0:1], 0, v[32:33]
	v_or_b32_e32 v32, 0x60, v144
	v_lshl_add_u64 v[42:43], s[40:41], 0, v[38:39]
	v_lshlrev_b64 v[34:35], 12, v[34:35]
	v_lshl_add_u64 v[38:39], s[44:45], 0, v[38:39]
	v_lshl_add_u64 v[32:33], s[0:1], 0, v[32:33]
	v_lshl_add_u64 v[42:43], v[42:43], 0, v[34:35]
	v_lshl_add_u64 v[34:35], v[38:39], 0, v[34:35]
	v_lshl_add_u64 v[46:47], v[34:35], 0, v[144:145]
	v_lshl_add_u64 v[44:45], v[42:43], 0, v[144:145]
	s_waitcnt vmcnt(0)
	flat_load_dwordx4 v[32:35], v[32:33]
	s_nop 0
	flat_load_dwordx4 v[36:39], v[36:37]
	s_nop 0
	flat_load_dwordx4 v[40:43], v[40:41]
	s_nop 0
	flat_load_dwordx4 v[56:59], v[56:57]
	s_nop 0
	global_load_dwordx4 v[60:63], v[50:51], off
	global_load_dwordx4 v[210:213], v[50:51], off offset:32
	global_load_dwordx4 v[214:217], v[50:51], off offset:64
	global_load_dwordx4 v[218:221], v[50:51], off offset:96
	global_load_dwordx4 v[222:225], v[46:47], off
	global_load_dwordx4 v[228:231], v[46:47], off offset:32
	global_load_dwordx4 v[232:235], v[46:47], off offset:64
	global_load_dwordx4 v[236:239], v[46:47], off offset:96
	s_waitcnt vmcnt(0) lgkmcnt(0)
	v_pk_fma_f32 v[16:17], v[16:17], v[56:57], v[60:61]
	v_pk_fma_f32 v[18:19], v[18:19], v[58:59], v[62:63]
	flat_store_dwordx4 v[48:49], v[16:19]
	v_pk_fma_f32 v[20:21], v[20:21], v[40:41], v[210:211]
	v_pk_fma_f32 v[22:23], v[22:23], v[42:43], v[212:213]
	flat_store_dwordx4 v[48:49], v[20:23] offset:32
	v_pk_fma_f32 v[24:25], v[24:25], v[36:37], v[214:215]
	v_pk_fma_f32 v[26:27], v[26:27], v[38:39], v[216:217]
	flat_store_dwordx4 v[48:49], v[24:27] offset:64
	v_pk_fma_f32 v[28:29], v[28:29], v[32:33], v[218:219]
	v_pk_fma_f32 v[30:31], v[30:31], v[34:35], v[220:221]
	flat_store_dwordx4 v[48:49], v[28:31] offset:96
	v_pk_fma_f32 v[0:1], v[0:1], v[56:57], v[222:223]
	v_pk_fma_f32 v[2:3], v[2:3], v[58:59], v[224:225]
	flat_store_dwordx4 v[44:45], v[0:3]
	v_pk_fma_f32 v[4:5], v[4:5], v[40:41], v[228:229]
	v_pk_fma_f32 v[6:7], v[6:7], v[42:43], v[230:231]
	flat_store_dwordx4 v[44:45], v[4:7] offset:32
	v_pk_fma_f32 v[8:9], v[8:9], v[36:37], v[232:233]
	v_pk_fma_f32 v[10:11], v[10:11], v[38:39], v[234:235]
	flat_store_dwordx4 v[44:45], v[8:11] offset:64
	v_pk_fma_f32 v[12:13], v[12:13], v[32:33], v[236:237]
	v_pk_fma_f32 v[14:15], v[14:15], v[34:35], v[238:239]
	flat_store_dwordx4 v[44:45], v[12:15] offset:96
	s_cbranch_scc1 .LBB0_31
